# rmsnorm phases (layer 0 and 1) hand-written: 8 row loads in flight, next row pair loaded before the current stores
# baseline (speedup 1.0000x reference)
; __device__ __forceinline__ int otid() { int t = threadIdx.x; asm volatile("" : "+v"(t)); return t; }
; __device__ __forceinline__ void phase_norm(const Params& p, int l) {
;   const int tid = otid(), wid = tid >> 6, lane = tid & 63;
;   const float* g = p.norm_g + l * 1024;
;   float4 gg[4];
; #pragma unroll
;   for (int i = 0; i < 4; ++i) gg[i] = *reinterpret_cast<const float4*>(g + (i * 64 + lane) * 4);
;   for (int row = (blockIdx.x * 8 + wid) * 2; row < NTOK; row += gridDim.x * 16) {
;     float4 v[2][4]; float ss[2] = {0.f, 0.f};
; #pragma unroll
;     for (int r = 0; r < 2; ++r) {
;       const int rr = row + r;
;       const float* x = (l == 0) ? (rr < NP ? p.xp + (long)rr * 1024 : p.xs + (long)(rr - NP) * 1024) : p.out + (long)rr * 1024;
; #pragma unroll
;       for (int i = 0; i < 4; ++i) v[r][i] = *reinterpret_cast<const float4*>(x + (i * 64 + lane) * 4);
;     }
.LBB0_59:
	s_waitcnt lgkmcnt(0)
	v_readlane_b32 s8, v248, 0
	v_readlane_b32 s9, v248, 1
	s_load_dwordx4 s[0:3], s[8:9], 0x0
	s_load_dwordx2 s[6:7], s[8:9], 0x30
	s_load_dwordx2 s[4:5], s[8:9], 0x98
	s_waitcnt lgkmcnt(0)
	s_sub_u32 s2, s2, 0x10000000
	s_subb_u32 s3, s3, 0
	v_and_b32_e32 v75, 63, v188
	v_xor_b32_e32 v1, 32, v75
	v_xor_b32_e32 v2, 16, v75
	v_xor_b32_e32 v3, 8, v75
	v_xor_b32_e32 v72, 4, v75
	v_xor_b32_e32 v73, 2, v75
	v_xor_b32_e32 v74, 1, v75
	v_lshlrev_b32_e32 v1, 2, v1
	v_lshlrev_b32_e32 v2, 2, v2
	v_lshlrev_b32_e32 v3, 2, v3
	v_lshlrev_b32_e32 v72, 2, v72
	v_lshlrev_b32_e32 v73, 2, v73
	v_lshlrev_b32_e32 v74, 2, v74
	v_lshlrev_b32_e32 v76, 3, v75
	v_lshlrev_b32_e32 v75, 4, v75
	v_lshrrev_b32_e32 v70, 6, v188
	v_mov_b32_e32 v77, 0x358637bd
	s_nop 0
	v_readfirstlane_b32 s8, v70
	global_load_dwordx4 v[4:7], v75, s[6:7]
	global_load_dwordx4 v[8:11], v75, s[6:7] offset:1024
	global_load_dwordx4 v[12:15], v75, s[6:7] offset:2048
	global_load_dwordx4 v[16:19], v75, s[6:7] offset:3072
	s_lshl_b32 s8, s8, 1
	s_lshl_b32 s6, s65, 4
	v_writelane_b32 v248, s6, 4
	s_lshl_b32 s9, s66, 4
	s_add_i32 s8, s8, s6
	s_mov_b32 s6, 0x3a800000
	s_lshl_b32 s7, s8, 12
	s_cmp_lt_u32 s8, 0x10000
	s_cselect_b32 s12, s0, s2
	s_cselect_b32 s13, s1, s3
	s_add_u32 s12, s12, s7
	s_addc_u32 s13, s13, 0
	s_add_u32 s14, s12, 0x1000
	s_addc_u32 s15, s13, 0
	global_load_dwordx4 v[20:23], v75, s[12:13]
	global_load_dwordx4 v[24:27], v75, s[12:13] offset:1024
	global_load_dwordx4 v[28:31], v75, s[12:13] offset:2048
	global_load_dwordx4 v[32:35], v75, s[12:13] offset:3072
	global_load_dwordx4 v[36:39], v75, s[14:15]
	global_load_dwordx4 v[40:43], v75, s[14:15] offset:1024
	global_load_dwordx4 v[44:47], v75, s[14:15] offset:2048
	global_load_dwordx4 v[48:51], v75, s[14:15] offset:3072
	s_lshl_b32 s7, s8, 11
	s_add_u32 s10, s4, s7
	s_addc_u32 s11, s5, 0
	s_waitcnt vmcnt(0)
; __device__ __forceinline__ unsigned pack2(float a, float b) { unsigned r; asm volatile("v_cvt_pk_bf16_f32 %0, %1, %2" : "=v"(r) : "v"(a), "v"(b)); return r; }
; __device__ __forceinline__ void phase_norm(const Params& p, int l) {
;     ...
; #pragma unroll
;     for (int r = 0; r < 2; ++r) {
; #pragma unroll
;       for (int i = 0; i < 4; ++i) ss[r] += v[r][i].x * v[r][i].x + v[r][i].y * v[r][i].y + v[r][i].z * v[r][i].z + v[r][i].w * v[r][i].w;
;     }
; #pragma unroll
;     for (int o = 32; o >= 1; o >>= 1) { ss[0] += __shfl_xor(ss[0], o); ss[1] += __shfl_xor(ss[1], o); }
; #pragma unroll
;     for (int r = 0; r < 2; ++r) {
;       const float rstd = rsqrtf(ss[r] * (1.f / 1024.f) + EPSV);
; #pragma unroll
;       for (int i = 0; i < 4; ++i) {
;         const int c = (i * 64 + lane) * 4;
;         uint2 o2;
;         o2.x = pack2(v[r][i].x * rstd * gg[i].x, v[r][i].y * rstd * gg[i].y);
;         o2.y = pack2(v[r][i].z * rstd * gg[i].z, v[r][i].w * rstd * gg[i].w);
;         *reinterpret_cast<uint2*>(p.h + (long)(row + r) * 1024 + c) = o2;
;       }
;     }
;   }
.Lnm0_loop:
	v_mul_f32_e32 v68, v20, v20
	v_fmac_f32_e32 v68, v21, v21
	v_fmac_f32_e32 v68, v22, v22
	v_fmac_f32_e32 v68, v23, v23
	v_fmac_f32_e32 v68, v24, v24
	v_fmac_f32_e32 v68, v25, v25
	v_fmac_f32_e32 v68, v26, v26
	v_fmac_f32_e32 v68, v27, v27
	v_fmac_f32_e32 v68, v28, v28
	v_fmac_f32_e32 v68, v29, v29
	v_fmac_f32_e32 v68, v30, v30
	v_fmac_f32_e32 v68, v31, v31
	v_fmac_f32_e32 v68, v32, v32
	v_fmac_f32_e32 v68, v33, v33
	v_fmac_f32_e32 v68, v34, v34
	v_fmac_f32_e32 v68, v35, v35
	v_mul_f32_e32 v69, v36, v36
	v_fmac_f32_e32 v69, v37, v37
	v_fmac_f32_e32 v69, v38, v38
	v_fmac_f32_e32 v69, v39, v39
	v_fmac_f32_e32 v69, v40, v40
	v_fmac_f32_e32 v69, v41, v41
	v_fmac_f32_e32 v69, v42, v42
	v_fmac_f32_e32 v69, v43, v43
	v_fmac_f32_e32 v69, v44, v44
	v_fmac_f32_e32 v69, v45, v45
	v_fmac_f32_e32 v69, v46, v46
	v_fmac_f32_e32 v69, v47, v47
	v_fmac_f32_e32 v69, v48, v48
	v_fmac_f32_e32 v69, v49, v49
	v_fmac_f32_e32 v69, v50, v50
	v_fmac_f32_e32 v69, v51, v51
	ds_bpermute_b32 v70, v1, v68
	ds_bpermute_b32 v71, v1, v69
	s_waitcnt lgkmcnt(0)
	v_add_f32_e32 v68, v68, v70
	v_add_f32_e32 v69, v69, v71
	ds_bpermute_b32 v70, v2, v68
	ds_bpermute_b32 v71, v2, v69
	s_waitcnt lgkmcnt(0)
	v_add_f32_e32 v68, v68, v70
	v_add_f32_e32 v69, v69, v71
	ds_bpermute_b32 v70, v3, v68
	ds_bpermute_b32 v71, v3, v69
	s_waitcnt lgkmcnt(0)
	v_add_f32_e32 v68, v68, v70
	v_add_f32_e32 v69, v69, v71
	ds_bpermute_b32 v70, v72, v68
	ds_bpermute_b32 v71, v72, v69
	s_waitcnt lgkmcnt(0)
	v_add_f32_e32 v68, v68, v70
	v_add_f32_e32 v69, v69, v71
	ds_bpermute_b32 v70, v73, v68
	ds_bpermute_b32 v71, v73, v69
	s_waitcnt lgkmcnt(0)
	v_add_f32_e32 v68, v68, v70
	v_add_f32_e32 v69, v69, v71
	ds_bpermute_b32 v70, v74, v68
	ds_bpermute_b32 v71, v74, v69
	s_waitcnt lgkmcnt(0)
	v_add_f32_e32 v68, v68, v70
	v_add_f32_e32 v69, v69, v71
	v_fma_f32 v68, v68, s6, v77
	v_fma_f32 v69, v69, s6, v77
	v_rsq_f32_e32 v68, v68
	v_rsq_f32_e32 v69, v69
	s_nop 0
	v_mul_f32_e32 v20, v20, v68
	v_mul_f32_e32 v21, v21, v68
	v_mul_f32_e32 v22, v22, v68
	v_mul_f32_e32 v23, v23, v68
	v_mul_f32_e32 v20, v4, v20
	v_mul_f32_e32 v21, v5, v21
	v_mul_f32_e32 v22, v6, v22
	v_mul_f32_e32 v23, v7, v23
	v_cvt_pk_bf16_f32 v52, v20, v21
	v_cvt_pk_bf16_f32 v53, v22, v23
	v_mul_f32_e32 v24, v24, v68
	v_mul_f32_e32 v25, v25, v68
	v_mul_f32_e32 v26, v26, v68
	v_mul_f32_e32 v27, v27, v68
	v_mul_f32_e32 v24, v8, v24
	v_mul_f32_e32 v25, v9, v25
	v_mul_f32_e32 v26, v10, v26
	v_mul_f32_e32 v27, v11, v27
	v_cvt_pk_bf16_f32 v54, v24, v25
	v_cvt_pk_bf16_f32 v55, v26, v27
	v_mul_f32_e32 v28, v28, v68
	v_mul_f32_e32 v29, v29, v68
	v_mul_f32_e32 v30, v30, v68
	v_mul_f32_e32 v31, v31, v68
	v_mul_f32_e32 v28, v12, v28
	v_mul_f32_e32 v29, v13, v29
	v_mul_f32_e32 v30, v14, v30
	v_mul_f32_e32 v31, v15, v31
	v_cvt_pk_bf16_f32 v56, v28, v29
	v_cvt_pk_bf16_f32 v57, v30, v31
	v_mul_f32_e32 v32, v32, v68
	v_mul_f32_e32 v33, v33, v68
	v_mul_f32_e32 v34, v34, v68
	v_mul_f32_e32 v35, v35, v68
	v_mul_f32_e32 v32, v16, v32
	v_mul_f32_e32 v33, v17, v33
	v_mul_f32_e32 v34, v18, v34
	v_mul_f32_e32 v35, v19, v35
	v_cvt_pk_bf16_f32 v58, v32, v33
	v_cvt_pk_bf16_f32 v59, v34, v35
	v_mul_f32_e32 v36, v36, v69
	v_mul_f32_e32 v37, v37, v69
	v_mul_f32_e32 v38, v38, v69
	v_mul_f32_e32 v39, v39, v69
	v_mul_f32_e32 v36, v4, v36
	v_mul_f32_e32 v37, v5, v37
	v_mul_f32_e32 v38, v6, v38
	v_mul_f32_e32 v39, v7, v39
	v_cvt_pk_bf16_f32 v60, v36, v37
	v_cvt_pk_bf16_f32 v61, v38, v39
	v_mul_f32_e32 v40, v40, v69
	v_mul_f32_e32 v41, v41, v69
	v_mul_f32_e32 v42, v42, v69
	v_mul_f32_e32 v43, v43, v69
	v_mul_f32_e32 v40, v8, v40
	v_mul_f32_e32 v41, v9, v41
	v_mul_f32_e32 v42, v10, v42
	v_mul_f32_e32 v43, v11, v43
	v_cvt_pk_bf16_f32 v62, v40, v41
	v_cvt_pk_bf16_f32 v63, v42, v43
	v_mul_f32_e32 v44, v44, v69
	v_mul_f32_e32 v45, v45, v69
	v_mul_f32_e32 v46, v46, v69
	v_mul_f32_e32 v47, v47, v69
	v_mul_f32_e32 v44, v12, v44
	v_mul_f32_e32 v45, v13, v45
	v_mul_f32_e32 v46, v14, v46
	v_mul_f32_e32 v47, v15, v47
	v_cvt_pk_bf16_f32 v64, v44, v45
	v_cvt_pk_bf16_f32 v65, v46, v47
	v_mul_f32_e32 v48, v48, v69
	v_mul_f32_e32 v49, v49, v69
	v_mul_f32_e32 v50, v50, v69
	v_mul_f32_e32 v51, v51, v69
	v_mul_f32_e32 v48, v16, v48
	v_mul_f32_e32 v49, v17, v49
	v_mul_f32_e32 v50, v18, v50
	v_mul_f32_e32 v51, v19, v51
	v_cvt_pk_bf16_f32 v66, v48, v49
	v_cvt_pk_bf16_f32 v67, v50, v51
	s_add_i32 s8, s8, s9
	s_cmp_lt_u32 s8, 0x10100
	s_cbranch_scc0 .Lnm0_last
	s_lshl_b32 s7, s8, 12
	s_cmp_lt_u32 s8, 0x10000
	s_cselect_b32 s12, s0, s2
	s_cselect_b32 s13, s1, s3
	s_add_u32 s12, s12, s7
	s_addc_u32 s13, s13, 0
	s_add_u32 s14, s12, 0x1000
	s_addc_u32 s15, s13, 0
	global_load_dwordx4 v[20:23], v75, s[12:13]
	global_load_dwordx4 v[24:27], v75, s[12:13] offset:1024
	global_load_dwordx4 v[28:31], v75, s[12:13] offset:2048
	global_load_dwordx4 v[32:35], v75, s[12:13] offset:3072
	global_load_dwordx4 v[36:39], v75, s[14:15]
	global_load_dwordx4 v[40:43], v75, s[14:15] offset:1024
	global_load_dwordx4 v[44:47], v75, s[14:15] offset:2048
	global_load_dwordx4 v[48:51], v75, s[14:15] offset:3072
	global_store_dwordx2 v76, v[52:53], s[10:11]
	global_store_dwordx2 v76, v[54:55], s[10:11] offset:512
	global_store_dwordx2 v76, v[56:57], s[10:11] offset:1024
	global_store_dwordx2 v76, v[58:59], s[10:11] offset:1536
	global_store_dwordx2 v76, v[60:61], s[10:11] offset:2048
	global_store_dwordx2 v76, v[62:63], s[10:11] offset:2560
	global_store_dwordx2 v76, v[64:65], s[10:11] offset:3072
	global_store_dwordx2 v76, v[66:67], s[10:11] offset:3584
	s_lshl_b32 s7, s8, 11
	s_add_u32 s10, s4, s7
	s_addc_u32 s11, s5, 0
	s_waitcnt vmcnt(8)
	s_branch .Lnm0_loop
.Lnm0_last:
	global_store_dwordx2 v76, v[52:53], s[10:11]
	global_store_dwordx2 v76, v[54:55], s[10:11] offset:512
	global_store_dwordx2 v76, v[56:57], s[10:11] offset:1024
	global_store_dwordx2 v76, v[58:59], s[10:11] offset:1536
	global_store_dwordx2 v76, v[60:61], s[10:11] offset:2048
	global_store_dwordx2 v76, v[62:63], s[10:11] offset:2560
	global_store_dwordx2 v76, v[64:65], s[10:11] offset:3072
	global_store_dwordx2 v76, v[66:67], s[10:11] offset:3584
	v_mbcnt_lo_u32_b32 v1, -1, 0

; __device__ __forceinline__ int otid() { int t = threadIdx.x; asm volatile("" : "+v"(t)); return t; }
; __device__ __forceinline__ void phase_norm(const Params& p, int l) {
;   const int tid = otid(), wid = tid >> 6, lane = tid & 63;
;   const float* g = p.norm_g + l * 1024;
;   float4 gg[4];
; #pragma unroll
;   for (int i = 0; i < 4; ++i) gg[i] = *reinterpret_cast<const float4*>(g + (i * 64 + lane) * 4);
;   for (int row = (blockIdx.x * 8 + wid) * 2; row < NTOK; row += gridDim.x * 16) {
;     float4 v[2][4]; float ss[2] = {0.f, 0.f};
; #pragma unroll
;     for (int r = 0; r < 2; ++r) {
;       const int rr = row + r;
;       const float* x = (l == 0) ? (rr < NP ? p.xp + (long)rr * 1024 : p.xs + (long)(rr - NP) * 1024) : p.out + (long)rr * 1024;
; #pragma unroll
;       for (int i = 0; i < 4; ++i) v[r][i] = *reinterpret_cast<const float4*>(x + (i * 64 + lane) * 4);
;     }
.LBB0_1070:
	s_or_b64 exec, exec, s[0:1]
	s_waitcnt lgkmcnt(0)
	v_mov_b32_e32 v0, v188
	s_barrier
	v_readlane_b32 s2, v248, 49
	v_readlane_b32 s3, v248, 50
	v_readlane_b32 s4, v248, 57
	v_readlane_b32 s5, v248, 58
	v_readlane_b32 s6, v248, 40
	v_readlane_b32 s7, v248, 41
	s_nop 3
	v_and_b32_e32 v75, 63, v188
	v_xor_b32_e32 v1, 32, v75
	v_xor_b32_e32 v2, 16, v75
	v_xor_b32_e32 v3, 8, v75
	v_xor_b32_e32 v72, 4, v75
	v_xor_b32_e32 v73, 2, v75
	v_xor_b32_e32 v74, 1, v75
	v_lshlrev_b32_e32 v1, 2, v1
	v_lshlrev_b32_e32 v2, 2, v2
	v_lshlrev_b32_e32 v3, 2, v3
	v_lshlrev_b32_e32 v72, 2, v72
	v_lshlrev_b32_e32 v73, 2, v73
	v_lshlrev_b32_e32 v74, 2, v74
	v_lshlrev_b32_e32 v190, 3, v75
	v_lshlrev_b32_e32 v75, 4, v75
	v_lshrrev_b32_e32 v70, 6, v188
	s_nop 0
	v_readfirstlane_b32 s8, v70
	global_load_dwordx4 v[4:7], v75, s[6:7]
	global_load_dwordx4 v[8:11], v75, s[6:7] offset:1024
	global_load_dwordx4 v[12:15], v75, s[6:7] offset:2048
	global_load_dwordx4 v[16:19], v75, s[6:7] offset:3072
	s_lshl_b32 s8, s8, 1
	v_readlane_b32 s6, v248, 4
	s_mov_b32 s9, s22
	s_add_i32 s8, s8, s6
	s_mov_b32 s6, 0x3a800000
	s_lshl_b32 s7, s8, 12
	s_add_u32 s12, s2, s7
	s_addc_u32 s13, s3, 0
	s_add_u32 s14, s12, 0x1000
	s_addc_u32 s15, s13, 0
	global_load_dwordx4 v[20:23], v75, s[12:13]
	global_load_dwordx4 v[24:27], v75, s[12:13] offset:1024
	global_load_dwordx4 v[28:31], v75, s[12:13] offset:2048
	global_load_dwordx4 v[32:35], v75, s[12:13] offset:3072
	global_load_dwordx4 v[36:39], v75, s[14:15]
	global_load_dwordx4 v[40:43], v75, s[14:15] offset:1024
	global_load_dwordx4 v[44:47], v75, s[14:15] offset:2048
	global_load_dwordx4 v[48:51], v75, s[14:15] offset:3072
	s_lshl_b32 s7, s8, 11
	s_add_u32 s10, s4, s7
	s_addc_u32 s11, s5, 0
	s_waitcnt vmcnt(0)
; __device__ __forceinline__ unsigned pack2(float a, float b) { unsigned r; asm volatile("v_cvt_pk_bf16_f32 %0, %1, %2" : "=v"(r) : "v"(a), "v"(b)); return r; }
; __device__ __forceinline__ void phase_norm(const Params& p, int l) {
;     ...
; #pragma unroll
;     for (int r = 0; r < 2; ++r) {
; #pragma unroll
;       for (int i = 0; i < 4; ++i) ss[r] += v[r][i].x * v[r][i].x + v[r][i].y * v[r][i].y + v[r][i].z * v[r][i].z + v[r][i].w * v[r][i].w;
;     }
; #pragma unroll
;     for (int o = 32; o >= 1; o >>= 1) { ss[0] += __shfl_xor(ss[0], o); ss[1] += __shfl_xor(ss[1], o); }
; #pragma unroll
;     for (int r = 0; r < 2; ++r) {
;       const float rstd = rsqrtf(ss[r] * (1.f / 1024.f) + EPSV);
; #pragma unroll
;       for (int i = 0; i < 4; ++i) {
;         const int c = (i * 64 + lane) * 4;
;         uint2 o2;
;         o2.x = pack2(v[r][i].x * rstd * gg[i].x, v[r][i].y * rstd * gg[i].y);
;         o2.y = pack2(v[r][i].z * rstd * gg[i].z, v[r][i].w * rstd * gg[i].w);
;         *reinterpret_cast<uint2*>(p.h + (long)(row + r) * 1024 + c) = o2;
;       }
;     }
;   }
.Lnm1_loop:
	v_mul_f32_e32 v68, v20, v20
	v_fmac_f32_e32 v68, v21, v21
	v_fmac_f32_e32 v68, v22, v22
	v_fmac_f32_e32 v68, v23, v23
	v_fmac_f32_e32 v68, v24, v24
	v_fmac_f32_e32 v68, v25, v25
	v_fmac_f32_e32 v68, v26, v26
	v_fmac_f32_e32 v68, v27, v27
	v_fmac_f32_e32 v68, v28, v28
	v_fmac_f32_e32 v68, v29, v29
	v_fmac_f32_e32 v68, v30, v30
	v_fmac_f32_e32 v68, v31, v31
	v_fmac_f32_e32 v68, v32, v32
	v_fmac_f32_e32 v68, v33, v33
	v_fmac_f32_e32 v68, v34, v34
	v_fmac_f32_e32 v68, v35, v35
	v_mul_f32_e32 v69, v36, v36
	v_fmac_f32_e32 v69, v37, v37
	v_fmac_f32_e32 v69, v38, v38
	v_fmac_f32_e32 v69, v39, v39
	v_fmac_f32_e32 v69, v40, v40
	v_fmac_f32_e32 v69, v41, v41
	v_fmac_f32_e32 v69, v42, v42
	v_fmac_f32_e32 v69, v43, v43
	v_fmac_f32_e32 v69, v44, v44
	v_fmac_f32_e32 v69, v45, v45
	v_fmac_f32_e32 v69, v46, v46
	v_fmac_f32_e32 v69, v47, v47
	v_fmac_f32_e32 v69, v48, v48
	v_fmac_f32_e32 v69, v49, v49
	v_fmac_f32_e32 v69, v50, v50
	v_fmac_f32_e32 v69, v51, v51
	ds_bpermute_b32 v70, v1, v68
	ds_bpermute_b32 v71, v1, v69
	s_waitcnt lgkmcnt(0)
	v_add_f32_e32 v68, v68, v70
	v_add_f32_e32 v69, v69, v71
	ds_bpermute_b32 v70, v2, v68
	ds_bpermute_b32 v71, v2, v69
	s_waitcnt lgkmcnt(0)
	v_add_f32_e32 v68, v68, v70
	v_add_f32_e32 v69, v69, v71
	ds_bpermute_b32 v70, v3, v68
	ds_bpermute_b32 v71, v3, v69
	s_waitcnt lgkmcnt(0)
	v_add_f32_e32 v68, v68, v70
	v_add_f32_e32 v69, v69, v71
	ds_bpermute_b32 v70, v72, v68
	ds_bpermute_b32 v71, v72, v69
	s_waitcnt lgkmcnt(0)
	v_add_f32_e32 v68, v68, v70
	v_add_f32_e32 v69, v69, v71
	ds_bpermute_b32 v70, v73, v68
	ds_bpermute_b32 v71, v73, v69
	s_waitcnt lgkmcnt(0)
	v_add_f32_e32 v68, v68, v70
	v_add_f32_e32 v69, v69, v71
	ds_bpermute_b32 v70, v74, v68
	ds_bpermute_b32 v71, v74, v69
	s_waitcnt lgkmcnt(0)
	v_add_f32_e32 v68, v68, v70
	v_add_f32_e32 v69, v69, v71
	v_fma_f32 v68, v68, s6, v192
	v_fma_f32 v69, v69, s6, v192
	v_rsq_f32_e32 v68, v68
	v_rsq_f32_e32 v69, v69
	s_nop 0
	v_mul_f32_e32 v20, v20, v68
	v_mul_f32_e32 v21, v21, v68
	v_mul_f32_e32 v22, v22, v68
	v_mul_f32_e32 v23, v23, v68
	v_mul_f32_e32 v20, v4, v20
	v_mul_f32_e32 v21, v5, v21
	v_mul_f32_e32 v22, v6, v22
	v_mul_f32_e32 v23, v7, v23
	v_cvt_pk_bf16_f32 v52, v20, v21
	v_cvt_pk_bf16_f32 v53, v22, v23
	v_mul_f32_e32 v24, v24, v68
	v_mul_f32_e32 v25, v25, v68
	v_mul_f32_e32 v26, v26, v68
	v_mul_f32_e32 v27, v27, v68
	v_mul_f32_e32 v24, v8, v24
	v_mul_f32_e32 v25, v9, v25
	v_mul_f32_e32 v26, v10, v26
	v_mul_f32_e32 v27, v11, v27
	v_cvt_pk_bf16_f32 v54, v24, v25
	v_cvt_pk_bf16_f32 v55, v26, v27
	v_mul_f32_e32 v28, v28, v68
	v_mul_f32_e32 v29, v29, v68
	v_mul_f32_e32 v30, v30, v68
	v_mul_f32_e32 v31, v31, v68
	v_mul_f32_e32 v28, v12, v28
	v_mul_f32_e32 v29, v13, v29
	v_mul_f32_e32 v30, v14, v30
	v_mul_f32_e32 v31, v15, v31
	v_cvt_pk_bf16_f32 v56, v28, v29
	v_cvt_pk_bf16_f32 v57, v30, v31
	v_mul_f32_e32 v32, v32, v68
	v_mul_f32_e32 v33, v33, v68
	v_mul_f32_e32 v34, v34, v68
	v_mul_f32_e32 v35, v35, v68
	v_mul_f32_e32 v32, v16, v32
	v_mul_f32_e32 v33, v17, v33
	v_mul_f32_e32 v34, v18, v34
	v_mul_f32_e32 v35, v19, v35
	v_cvt_pk_bf16_f32 v58, v32, v33
	v_cvt_pk_bf16_f32 v59, v34, v35
	v_mul_f32_e32 v36, v36, v69
	v_mul_f32_e32 v37, v37, v69
	v_mul_f32_e32 v38, v38, v69
	v_mul_f32_e32 v39, v39, v69
	v_mul_f32_e32 v36, v4, v36
	v_mul_f32_e32 v37, v5, v37
	v_mul_f32_e32 v38, v6, v38
	v_mul_f32_e32 v39, v7, v39
	v_cvt_pk_bf16_f32 v60, v36, v37
	v_cvt_pk_bf16_f32 v61, v38, v39
	v_mul_f32_e32 v40, v40, v69
	v_mul_f32_e32 v41, v41, v69
	v_mul_f32_e32 v42, v42, v69
	v_mul_f32_e32 v43, v43, v69
	v_mul_f32_e32 v40, v8, v40
	v_mul_f32_e32 v41, v9, v41
	v_mul_f32_e32 v42, v10, v42
	v_mul_f32_e32 v43, v11, v43
	v_cvt_pk_bf16_f32 v62, v40, v41
	v_cvt_pk_bf16_f32 v63, v42, v43
	v_mul_f32_e32 v44, v44, v69
	v_mul_f32_e32 v45, v45, v69
	v_mul_f32_e32 v46, v46, v69
	v_mul_f32_e32 v47, v47, v69
	v_mul_f32_e32 v44, v12, v44
	v_mul_f32_e32 v45, v13, v45
	v_mul_f32_e32 v46, v14, v46
	v_mul_f32_e32 v47, v15, v47
	v_cvt_pk_bf16_f32 v64, v44, v45
	v_cvt_pk_bf16_f32 v65, v46, v47
	v_mul_f32_e32 v48, v48, v69
	v_mul_f32_e32 v49, v49, v69
	v_mul_f32_e32 v50, v50, v69
	v_mul_f32_e32 v51, v51, v69
	v_mul_f32_e32 v48, v16, v48
	v_mul_f32_e32 v49, v17, v49
	v_mul_f32_e32 v50, v18, v50
	v_mul_f32_e32 v51, v19, v51
	v_cvt_pk_bf16_f32 v66, v48, v49
	v_cvt_pk_bf16_f32 v67, v50, v51
	s_add_i32 s8, s8, s9
	s_cmp_lt_u32 s8, 0x10100
	s_cbranch_scc0 .Lnm1_last
	s_lshl_b32 s7, s8, 12
	s_add_u32 s12, s2, s7
	s_addc_u32 s13, s3, 0
	s_add_u32 s14, s12, 0x1000
	s_addc_u32 s15, s13, 0
	global_load_dwordx4 v[20:23], v75, s[12:13]
	global_load_dwordx4 v[24:27], v75, s[12:13] offset:1024
	global_load_dwordx4 v[28:31], v75, s[12:13] offset:2048
	global_load_dwordx4 v[32:35], v75, s[12:13] offset:3072
	global_load_dwordx4 v[36:39], v75, s[14:15]
	global_load_dwordx4 v[40:43], v75, s[14:15] offset:1024
	global_load_dwordx4 v[44:47], v75, s[14:15] offset:2048
	global_load_dwordx4 v[48:51], v75, s[14:15] offset:3072
	global_store_dwordx2 v190, v[52:53], s[10:11]
	global_store_dwordx2 v190, v[54:55], s[10:11] offset:512
	global_store_dwordx2 v190, v[56:57], s[10:11] offset:1024
	global_store_dwordx2 v190, v[58:59], s[10:11] offset:1536
	global_store_dwordx2 v190, v[60:61], s[10:11] offset:2048
	global_store_dwordx2 v190, v[62:63], s[10:11] offset:2560
	global_store_dwordx2 v190, v[64:65], s[10:11] offset:3072
	global_store_dwordx2 v190, v[66:67], s[10:11] offset:3584
	s_lshl_b32 s7, s8, 11
	s_add_u32 s10, s4, s7
	s_addc_u32 s11, s5, 0
	s_waitcnt vmcnt(8)
	s_branch .Lnm1_loop
.Lnm1_last:
	global_store_dwordx2 v190, v[52:53], s[10:11]
	global_store_dwordx2 v190, v[54:55], s[10:11] offset:512
	global_store_dwordx2 v190, v[56:57], s[10:11] offset:1024
	global_store_dwordx2 v190, v[58:59], s[10:11] offset:1536
	global_store_dwordx2 v190, v[60:61], s[10:11] offset:2048
	global_store_dwordx2 v190, v[62:63], s[10:11] offset:2560
	global_store_dwordx2 v190, v[64:65], s[10:11] offset:3072
	global_store_dwordx2 v190, v[66:67], s[10:11] offset:3584
	s_mov_b32 s20, 0x800000
